# DSA: softmax max by DPP, xor-16 norm sums by v_permlane16_swap (LDS round trips removed)
# speedup vs baseline: 1.0378x; 1.0090x over previous
; #define LAS __attribute__((address_space(3)))
;     ...
;           for (int jj = 0; jj < 4; ++jj) {
;               const int rho = jj * 16 + c16, slot = b * 64 + rho;
;               f32x4 a = {0.f, 0.f, 0.f, 0.f}; float ss = 0.f;
; #pragma unroll
;               for (int ks = 0; ks < 4; ++ks) {
; #pragma unroll
;                   for (int e = 0; e < 4; ++e) asm("v_dot2_f32_bf16 %0, %1, %1, %0" : "+v"(ss) : "v"(w[jj][ks][e]));
;                   a = __builtin_amdgcn_mfma_f32_16x16x32_bf16(qa[ks], *reinterpret_cast<const bf16x8*>(&w[jj][ks]), a, 0, 0, 0);
;                   *(LAS u32x4*)(wbase + rho * 256 + (((ks * 4 + quad) ^ fsw) << 4)) = w[jj][ks]; }
;               ss += __shfl_xor(ss, 16); ss += __shfl_xor(ss, 32);
;               const float rstd = rsqrtf(ss * (1.f / 128.f) + EPS);
;               const float av = quad == 0 ? a[0] : (quad == 1 ? a[1] : (quad == 2 ? a[2] : a[3]));
;               rsv[jj] = rstd; lgv[jj] = (slot < kcount) ? av * rstd * 0.08838834764831845f : -__builtin_inff();
;           }
.LBB0_928:
	v_mov_b32_e32 v118, 0
	s_waitcnt vmcnt(13)
	v_dot2_f32_bf16 v118, v26, v26, v118
	v_add_u32_e32 v0, v146, v147
	v_dot2_f32_bf16 v118, v27, v27, v118
	ds_write_b128 v0, v[26:29]
	v_dot2_f32_bf16 v118, v28, v28, v118
	v_add_u32_e32 v0, v146, v148
	v_dot2_f32_bf16 v118, v29, v29, v118
	ds_write_b128 v0, v[18:21]
	v_dot2_f32_bf16 v118, v18, v18, v118
	v_add_u32_e32 v0, v146, v149
	v_dot2_f32_bf16 v118, v19, v19, v118
	ds_write_b128 v0, v[22:25]
	v_dot2_f32_bf16 v118, v20, v20, v118
	v_add_u32_e32 v0, v146, v150
	v_dot2_f32_bf16 v118, v21, v21, v118
	v_and_b32_e32 v119, 64, v206
	v_dot2_f32_bf16 v118, v22, v22, v118
	s_waitcnt vmcnt(12)
	ds_write_b128 v0, v[30:33]
	v_dot2_f32_bf16 v118, v23, v23, v118
	v_dot2_f32_bf16 v118, v24, v24, v118
	v_add_u32_e32 v158, 64, v119
	v_dot2_f32_bf16 v118, v25, v25, v118
	v_dot2_f32_bf16 v118, v30, v30, v118
	v_mfma_f32_16x16x32_bf16 v[114:117], v[2:5], v[26:29], 0
	v_dot2_f32_bf16 v118, v31, v31, v118
	v_dot2_f32_bf16 v118, v32, v32, v118
	v_dot2_f32_bf16 v118, v33, v33, v118
	v_mfma_f32_16x16x32_bf16 v[114:117], v[6:9], v[18:21], v[114:117]
	s_nop 1
	v_mov_b32_e32 v119, v118
	s_nop 1
	v_permlane16_swap_b32_e32 v118, v119
	v_add_f32_e32 v161, v118, v119
	v_xor_b32_e32 v118, 32, v206
	v_mfma_f32_16x16x32_bf16 v[114:117], v[10:13], v[22:25], v[114:117]
	v_cmp_lt_i32_e32 vcc, v118, v158
	s_nop 1
	v_cndmask_b32_e32 v118, v206, v118, vcc
	v_lshlrev_b32_e32 v122, 2, v118
	ds_bpermute_b32 v172, v122, v161
	v_mfma_f32_16x16x32_bf16 v[114:117], v[14:17], v[30:33], v[114:117]
	v_cmp_lt_i32_e32 vcc, 0, v128
	s_and_saveexec_b64 s[0:1], vcc
	s_xor_b64 s[0:1], exec, s[0:1]
	s_cbranch_execz .LBB0_932
	v_cmp_ne_u32_e32 vcc, 1, v128
	s_nop 2
	v_mov_b32_e32 v114, v115
	s_and_saveexec_b64 s[20:21], vcc
	s_xor_b64 s[20:21], exec, s[20:21]
	v_cndmask_b32_e64 v114, v117, v116, s[40:41]
	s_andn2_saveexec_b64 s[20:21], s[20:21]
	s_or_b64 exec, exec, s[20:21]
.LBB0_932:
	s_andn2_saveexec_b64 s[0:1], s[0:1]
	s_or_b64 exec, exec, s[0:1]
	s_nop 1
	v_mov_b32_e32 v115, 0
	s_waitcnt vmcnt(9)
	v_dot2_f32_bf16 v115, v42, v42, v115
	v_mfma_f32_16x16x32_bf16 v[116:119], v[2:5], v[42:45], 0
	v_dot2_f32_bf16 v115, v43, v43, v115
	v_add_u32_e32 v120, v151, v147
	v_dot2_f32_bf16 v115, v44, v44, v115
	ds_write_b128 v120, v[42:45]
	v_dot2_f32_bf16 v115, v45, v45, v115
	v_add_u32_e32 v120, v151, v148
	v_dot2_f32_bf16 v115, v34, v34, v115
	ds_write_b128 v120, v[34:37]
	v_dot2_f32_bf16 v115, v35, v35, v115
	v_add_u32_e32 v120, v151, v149
	v_dot2_f32_bf16 v115, v36, v36, v115
	v_mfma_f32_16x16x32_bf16 v[116:119], v[6:9], v[34:37], v[116:119]
	v_dot2_f32_bf16 v115, v37, v37, v115
	ds_write_b128 v120, v[38:41]
	v_dot2_f32_bf16 v115, v38, v38, v115
	v_add_u32_e32 v120, v151, v150
	v_dot2_f32_bf16 v115, v39, v39, v115
	s_waitcnt vmcnt(8)
	ds_write_b128 v120, v[46:49]
	v_dot2_f32_bf16 v115, v40, v40, v115
	v_mfma_f32_16x16x32_bf16 v[116:119], v[10:13], v[38:41], v[116:119]
	v_dot2_f32_bf16 v115, v41, v41, v115
	v_cmp_lt_i32_e32 vcc, 0, v128
	v_dot2_f32_bf16 v115, v46, v46, v115
	v_mfma_f32_16x16x32_bf16 v[116:119], v[14:17], v[46:49], v[116:119]
	v_dot2_f32_bf16 v115, v47, v47, v115
	s_nop 0
	v_dot2_f32_bf16 v115, v48, v48, v115
	s_nop 0
	v_dot2_f32_bf16 v115, v49, v49, v115
	s_nop 2
	v_mov_b32_e32 v120, v115
	s_nop 1
	v_permlane16_swap_b32_e32 v115, v120
	v_add_f32_e32 v115, v115, v120
	ds_bpermute_b32 v173, v122, v115
	s_and_saveexec_b64 s[0:1], vcc
	s_xor_b64 s[0:1], exec, s[0:1]
	s_cbranch_execz .LBB0_936
	v_cmp_ne_u32_e32 vcc, 1, v128
	v_mov_b32_e32 v116, v117
	s_and_saveexec_b64 s[20:21], vcc
	s_xor_b64 s[20:21], exec, s[20:21]
	v_cndmask_b32_e64 v116, v119, v118, s[40:41]
	s_andn2_saveexec_b64 s[20:21], s[20:21]
	s_or_b64 exec, exec, s[20:21]
; #define LAS __attribute__((address_space(3)))
;     ...
;           for (int jj = 0; jj < 4; ++jj) {
;               const int rho = jj * 16 + c16, slot = b * 64 + rho;
;               f32x4 a = {0.f, 0.f, 0.f, 0.f}; float ss = 0.f;
; #pragma unroll
;               for (int ks = 0; ks < 4; ++ks) {
; #pragma unroll
;                   for (int e = 0; e < 4; ++e) asm("v_dot2_f32_bf16 %0, %1, %1, %0" : "+v"(ss) : "v"(w[jj][ks][e]));
;                   a = __builtin_amdgcn_mfma_f32_16x16x32_bf16(qa[ks], *reinterpret_cast<const bf16x8*>(&w[jj][ks]), a, 0, 0, 0);
;                   *(LAS u32x4*)(wbase + rho * 256 + (((ks * 4 + quad) ^ fsw) << 4)) = w[jj][ks]; }
;               ss += __shfl_xor(ss, 16); ss += __shfl_xor(ss, 32);
;               const float rstd = rsqrtf(ss * (1.f / 128.f) + EPS);
;               const float av = quad == 0 ? a[0] : (quad == 1 ? a[1] : (quad == 2 ? a[2] : a[3]));
;               rsv[jj] = rstd; lgv[jj] = (slot < kcount) ? av * rstd * 0.08838834764831845f : -__builtin_inff();
;           }
.LBB0_936:
	s_andn2_saveexec_b64 s[0:1], s[0:1]
	s_or_b64 exec, exec, s[0:1]
	v_mov_b32_e32 v117, 0
	s_waitcnt vmcnt(5)
	v_dot2_f32_bf16 v117, v58, v58, v117
	v_mfma_f32_16x16x32_bf16 v[118:121], v[2:5], v[58:61], 0
	v_dot2_f32_bf16 v117, v59, v59, v117
	v_add_u32_e32 v123, v152, v147
	v_dot2_f32_bf16 v117, v60, v60, v117
	ds_write_b128 v123, v[58:61]
	v_dot2_f32_bf16 v117, v61, v61, v117
	v_add_u32_e32 v123, v152, v148
	v_dot2_f32_bf16 v117, v50, v50, v117
	ds_write_b128 v123, v[50:53]
	v_dot2_f32_bf16 v117, v51, v51, v117
	v_add_u32_e32 v123, v152, v149
	v_dot2_f32_bf16 v117, v52, v52, v117
	v_mfma_f32_16x16x32_bf16 v[118:121], v[6:9], v[50:53], v[118:121]
	v_dot2_f32_bf16 v117, v53, v53, v117
	ds_write_b128 v123, v[54:57]
	v_dot2_f32_bf16 v117, v54, v54, v117
	v_add_u32_e32 v123, v152, v150
	v_dot2_f32_bf16 v117, v55, v55, v117
	s_waitcnt vmcnt(4)
	ds_write_b128 v123, v[62:65]
	v_dot2_f32_bf16 v117, v56, v56, v117
	v_mfma_f32_16x16x32_bf16 v[118:121], v[10:13], v[54:57], v[118:121]
	v_dot2_f32_bf16 v117, v57, v57, v117
	v_cmp_lt_i32_e32 vcc, 0, v128
	v_dot2_f32_bf16 v117, v62, v62, v117
	v_mfma_f32_16x16x32_bf16 v[118:121], v[14:17], v[62:65], v[118:121]
	v_dot2_f32_bf16 v117, v63, v63, v117
	s_nop 0
	v_dot2_f32_bf16 v117, v64, v64, v117
	s_nop 0
	v_dot2_f32_bf16 v117, v65, v65, v117
	s_nop 2
	v_mov_b32_e32 v123, v117
	s_nop 1
	v_permlane16_swap_b32_e32 v117, v123
	v_add_f32_e32 v117, v117, v123
	ds_bpermute_b32 v174, v122, v117
	s_and_saveexec_b64 s[0:1], vcc
	s_xor_b64 s[0:1], exec, s[0:1]
	s_cbranch_execz .LBB0_940
	v_cmp_ne_u32_e32 vcc, 1, v128
	v_mov_b32_e32 v118, v119
	s_and_saveexec_b64 s[20:21], vcc
	s_xor_b64 s[20:21], exec, s[20:21]
	v_cndmask_b32_e64 v118, v121, v120, s[40:41]
	s_andn2_saveexec_b64 s[20:21], s[20:21]
	s_or_b64 exec, exec, s[20:21]
.LBB0_940:
	s_andn2_saveexec_b64 s[0:1], s[0:1]
	s_or_b64 exec, exec, s[0:1]
	v_mov_b32_e32 v119, 0
	s_waitcnt vmcnt(1)
	v_dot2_f32_bf16 v119, v74, v74, v119
	v_mfma_f32_16x16x32_bf16 v[176:179], v[2:5], v[74:77], 0
	v_dot2_f32_bf16 v119, v75, v75, v119
	v_add_u32_e32 v120, v153, v147
	v_dot2_f32_bf16 v119, v76, v76, v119
	v_mfma_f32_16x16x32_bf16 v[176:179], v[6:9], v[66:69], v[176:179]
	v_dot2_f32_bf16 v119, v77, v77, v119
	ds_write_b128 v120, v[74:77]
	v_dot2_f32_bf16 v119, v66, v66, v119
	v_mfma_f32_16x16x32_bf16 v[176:179], v[10:13], v[70:73], v[176:179]
	v_dot2_f32_bf16 v119, v67, v67, v119
	v_add_u32_e32 v120, v153, v148
	v_dot2_f32_bf16 v119, v68, v68, v119
	ds_write_b128 v120, v[66:69]
	v_dot2_f32_bf16 v119, v69, v69, v119
	v_add_u32_e32 v120, v153, v149
	v_dot2_f32_bf16 v119, v70, v70, v119
	ds_write_b128 v120, v[70:73]
	v_dot2_f32_bf16 v119, v71, v71, v119
	v_cmp_lt_i32_e32 vcc, 0, v128
	v_dot2_f32_bf16 v119, v72, v72, v119
	s_nop 0
	v_dot2_f32_bf16 v119, v73, v73, v119
	s_waitcnt vmcnt(0)
	v_dot2_f32_bf16 v119, v78, v78, v119
	s_nop 0
	v_dot2_f32_bf16 v119, v79, v79, v119
	s_nop 0
	v_dot2_f32_bf16 v119, v80, v80, v119
	s_nop 0
	v_dot2_f32_bf16 v119, v81, v81, v119
	s_nop 2
	v_mov_b32_e32 v0, v119
	s_nop 1
	v_permlane16_swap_b32_e32 v119, v0
	v_add_f32_e32 v119, v119, v0
	ds_bpermute_b32 v175, v122, v119
	v_mfma_f32_16x16x32_bf16 v[120:123], v[14:17], v[78:81], v[176:179]
	v_add_u32_e32 v0, v153, v150
	ds_write_b128 v0, v[78:81]
	s_and_saveexec_b64 s[0:1], vcc
	s_xor_b64 s[0:1], exec, s[0:1]
	s_cbranch_execz .LBB0_944
	v_cmp_ne_u32_e32 vcc, 1, v128
	s_nop 1
	v_mov_b32_e32 v120, v121
	s_and_saveexec_b64 s[20:21], vcc
	s_xor_b64 s[20:21], exec, s[20:21]
	v_cndmask_b32_e64 v120, v123, v122, s[40:41]
	s_andn2_saveexec_b64 s[20:21], s[20:21]
	s_or_b64 exec, exec, s[20:21]

; #define LAS __attribute__((address_space(3)))
; __device__ __forceinline__ u16 f2bf(float f) { return (u16)(cvtpk(f, 0.f) & 0xffffu); }
;     ...
;               ss += __shfl_xor(ss, 16); ss += __shfl_xor(ss, 32);
;               const float rstd = rsqrtf(ss * (1.f / 128.f) + EPS);
;               const float av = quad == 0 ? a[0] : (quad == 1 ? a[1] : (quad == 2 ? a[2] : a[3]));
;               rsv[jj] = rstd; lgv[jj] = (slot < kcount) ? av * rstd * 0.08838834764831845f : -__builtin_inff();
;           }
;           if (b + 1 < nb) gl(b + 1);
;           float mx = fmaxf(fmaxf(lgv[0], lgv[1]), fmaxf(lgv[2], lgv[3]));
; #pragma unroll
;           for (int o = 1; o < 16; o <<= 1) mx = fmaxf(mx, __shfl_xor(mx, o));
;           const float mnew = fmaxf(mrun, mx), alpha = __expf(mrun - mnew); mrun = mnew;
;           float ps = 0.f;
; #pragma unroll
;           for (int jj = 0; jj < 4; ++jj) { const float pe = __expf(lgv[jj] - mnew); ps += pe; pbT[quad * 64 + jj * 16 + c16] = f2bf(pe * rsv[jj]); }
;           lsum = lsum * alpha + ps;
;           if (c16 == 0) alf[quad] = alpha;
;           const f32x4 al4 = *(const LAS f32x4*)alf;
.LBB0_946:
	s_waitcnt lgkmcnt(1)
	v_add_f32_e32 v119, v119, v175
	v_fmamk_f32 v119, v119, 0x3c000000, v199
	v_cmp_gt_f32_e32 vcc, s85, v119
	v_mul_f32_e32 v121, 0x4b800000, v119
	v_add_u32_e32 v0, 48, v157
	v_cndmask_b32_e32 v119, v119, v121, vcc
	v_rsq_f32_e32 v119, v119
	v_add_f32_e32 v117, v117, v174
	v_fmamk_f32 v117, v117, 0x3c000000, v199
	v_add_f32_e32 v115, v115, v173
	v_mul_f32_e32 v121, 0x45800000, v119
	v_cndmask_b32_e32 v122, v119, v121, vcc
	v_cmp_gt_i32_e32 vcc, s22, v0
	v_mul_f32_e32 v0, v122, v120
	v_mul_f32_e32 v0, 0x3db504f3, v0
	v_cndmask_b32_e32 v121, v208, v0, vcc
	v_cmp_gt_f32_e32 vcc, s85, v117
	v_mul_f32_e32 v119, 0x4b800000, v117
	v_add_u32_e32 v0, 32, v157
	v_cndmask_b32_e32 v117, v117, v119, vcc
	v_rsq_f32_e32 v117, v117
	v_fmamk_f32 v115, v115, 0x3c000000, v199
	v_mul_f32_e32 v119, 0x45800000, v117
	v_cndmask_b32_e32 v123, v117, v119, vcc
	v_cmp_gt_i32_e32 vcc, s22, v0
	v_mul_f32_e32 v0, v123, v118
	v_mul_f32_e32 v0, 0x3db504f3, v0
	v_cndmask_b32_e32 v120, v208, v0, vcc
	v_cmp_gt_f32_e32 vcc, s85, v115
	v_mul_f32_e32 v117, 0x4b800000, v115
	v_add_u32_e32 v0, 16, v157
	v_cndmask_b32_e32 v115, v115, v117, vcc
	v_rsq_f32_e32 v115, v115
	s_nop 0
	v_mul_f32_e32 v117, 0x45800000, v115
	v_cndmask_b32_e32 v125, v115, v117, vcc
	v_cmp_gt_i32_e32 vcc, s22, v0
	v_mul_f32_e32 v0, v125, v116
	v_mul_f32_e32 v0, 0x3db504f3, v0
	v_cndmask_b32_e32 v119, v208, v0, vcc
	v_add_f32_e32 v0, v161, v172
	v_fmamk_f32 v0, v0, 0x3c000000, v199
	v_cmp_gt_f32_e32 vcc, s85, v0
	v_mul_f32_e32 v115, 0x4b800000, v0
	s_nop 0
	v_cndmask_b32_e32 v0, v0, v115, vcc
	v_rsq_f32_e32 v0, v0
	s_nop 0
	v_mul_f32_e32 v115, 0x45800000, v0
	v_cndmask_b32_e32 v161, v0, v115, vcc
	v_mul_f32_e32 v0, v161, v114
	v_cmp_gt_i32_e32 vcc, s22, v157
	v_mul_f32_e32 v0, 0x3db504f3, v0
	s_nop 0
	v_cndmask_b32_e32 v118, v208, v0, vcc
	v_max_f32_e32 v0, v120, v121
	v_max3_f32 v114, v118, v119, v0
	s_nop 1
	v_max_f32_dpp v115, v114, v114 quad_perm:[1,0,3,2] row_mask:0xf bank_mask:0xf
	s_nop 1
	v_max_f32_dpp v116, v115, v115 quad_perm:[2,3,0,1] row_mask:0xf bank_mask:0xf
	s_nop 1
	v_max_f32_dpp v117, v116, v116 row_ror:4 row_mask:0xf bank_mask:0xf
	s_nop 1
	v_max_f32_dpp v172, v117, v117 row_ror:8 row_mask:0xf bank_mask:0xf
	v_xor_b32_e32 v0, 1, v206
	v_xor_b32_e32 v114, 2, v206
	v_xor_b32_e32 v115, 4, v206
	v_xor_b32_e32 v116, 8, v206
	v_max3_f32 v117, v160, v117, v172
	v_sub_f32_e32 v118, v118, v117
	v_sub_f32_e32 v119, v119, v117
	v_sub_f32_e32 v120, v120, v117
	v_sub_f32_e32 v121, v121, v117
	v_mul_f32_e32 v118, 0x3fb8aa3b, v118
	v_mul_f32_e32 v119, 0x3fb8aa3b, v119
	v_mul_f32_e32 v120, 0x3fb8aa3b, v120
	v_mul_f32_e32 v121, 0x3fb8aa3b, v121
	v_exp_f32_e32 v118, v118
	v_exp_f32_e32 v119, v119
	v_exp_f32_e32 v120, v120
	v_exp_f32_e32 v121, v121
	v_sub_f32_e32 v160, v160, v117
	v_mul_f32_e32 v161, v161, v118
	v_mul_f32_e32 v125, v125, v119
	v_mul_f32_e32 v123, v123, v120
	v_mul_f32_e32 v122, v122, v121
	v_mul_f32_e32 v160, 0x3fb8aa3b, v160
	v_cvt_pk_bf16_f32 v161, v161, v1
	ds_write_b16 v155, v161 offset:1024
	v_cvt_pk_bf16_f32 v125, v125, v1
	ds_write_b16 v155, v125 offset:1056
	v_cvt_pk_bf16_f32 v123, v123, v1
	ds_write_b16 v155, v123 offset:1088
	v_cvt_pk_bf16_f32 v122, v122, v1
	ds_write_b16 v155, v122 offset:1120
	v_exp_f32_e32 v122, v160
	s_and_saveexec_b64 s[0:1], s[38:39]
	ds_write_b32 v129, v122 offset:640
	s_or_b64 exec, exec, s[0:1]
	v_add_f32_e32 v118, 0, v118
	v_add_f32_e32 v118, v119, v118
	v_add_f32_e32 v118, v120, v118
	v_add_f32_e32 v118, v121, v118
	v_mov_b32_e32 v119, s56
	v_fmac_f32_e32 v118, v159, v122
	ds_read_b128 v[120:123], v119 offset:640
	v_add_u32_e32 v154, 0x80, v154
	v_add_u32_e32 v157, 64, v157
	s_cmp_eq_u32 s23, s24
	s_waitcnt lgkmcnt(0)
; #define LAS __attribute__((address_space(3)))
;     ...
;           const f32x4 al4 = *(const LAS f32x4*)alf;
; #pragma unroll
;           for (int c = 0; c < 8; ++c) oacc[c] *= al4;
; #pragma unroll
;           for (int ks = 0; ks < 2; ++ks) {
;               const bf16x8 pf = *(const LAS bf16x8*)(pbT + (c16 & 3) * 64 + ks * 32 + quad * 8);
;               u16x4 t0[8], t1[8];
;     ...
;               if (ks == 0) { TRR8(t0, 0, 0); TRR8(t1, 1, 0); } else { TRR8(t0, 0, 8192); TRR8(t1, 1, 8192); }
;     ...
; #pragma unroll
;               for (int c = 0; c < 8; ++c) {
;                   const bf16x8 bf = {(short)t0[c][0], (short)t0[c][1], (short)t0[c][2], (short)t0[c][3], (short)t1[c][0], (short)t1[c][1], (short)t1[c][2], (short)t1[c][3]};
;                   oacc[c] = __builtin_amdgcn_mfma_f32_16x16x32_bf16(pf, bf, oacc[c], 0, 0, 0);
;               }
;           }
	v_pk_mul_f32 v[174:175], v[92:93], v[122:123]
	v_pk_mul_f32 v[172:173], v[90:91], v[120:121]
	v_pk_mul_f32 v[92:93], v[96:97], v[122:123]
	v_pk_mul_f32 v[90:91], v[94:95], v[120:121]
	ds_read_b128 v[94:97], v156 offset:1024
	v_pk_mul_f32 v[106:107], v[106:107], v[120:121]
	v_pk_mul_f32 v[110:111], v[110:111], v[120:121]
	v_pk_mul_f32 v[176:177], v[82:83], v[120:121]
	v_pk_mul_f32 v[182:183], v[86:87], v[120:121]
	v_pk_mul_f32 v[86:87], v[102:103], v[120:121]
	v_pk_mul_f32 v[82:83], v[98:99], v[120:121]
	ds_read_b64_tr_b16 v[216:217], v130 offset:0
	ds_read_b64_tr_b16 v[212:213], v131 offset:0
	ds_read_b64_tr_b16 v[194:195], v132 offset:0
	ds_read_b64_tr_b16 v[190:191], v133 offset:0
	ds_read_b64_tr_b16 v[186:187], v134 offset:0
	ds_read_b64_tr_b16 v[120:121], v135 offset:0
	ds_read_b64_tr_b16 v[102:103], v136 offset:0
	ds_read_b64_tr_b16 v[98:99], v137 offset:0
	s_waitcnt lgkmcnt(0)
	v_pk_mul_f32 v[108:109], v[108:109], v[122:123]
	v_pk_mul_f32 v[112:113], v[112:113], v[122:123]
	v_pk_mul_f32 v[178:179], v[84:85], v[122:123]
	v_pk_mul_f32 v[184:185], v[88:89], v[122:123]
	v_pk_mul_f32 v[88:89], v[104:105], v[122:123]
	v_pk_mul_f32 v[84:85], v[100:101], v[122:123]
	ds_read_b64_tr_b16 v[218:219], v138 offset:0
	ds_read_b64_tr_b16 v[214:215], v139 offset:0
	ds_read_b64_tr_b16 v[196:197], v140 offset:0
	ds_read_b64_tr_b16 v[192:193], v141 offset:0
	ds_read_b64_tr_b16 v[188:189], v142 offset:0
	ds_read_b64_tr_b16 v[122:123], v143 offset:0
	ds_read_b64_tr_b16 v[104:105], v144 offset:0
	ds_read_b64_tr_b16 v[100:101], v145 offset:0
	s_waitcnt lgkmcnt(0)
	ds_read_b128 v[220:223], v156 offset:1088
	s_waitcnt lgkmcnt(1)
	v_mfma_f32_16x16x32_bf16 v[106:109], v[94:97], v[216:219], v[106:109]
	v_mfma_f32_16x16x32_bf16 v[110:113], v[94:97], v[212:215], v[110:113]
	v_mfma_f32_16x16x32_bf16 v[172:175], v[94:97], v[194:197], v[172:175]
	v_mfma_f32_16x16x32_bf16 v[176:179], v[94:97], v[190:193], v[176:179]
	v_mfma_f32_16x16x32_bf16 v[182:185], v[94:97], v[186:189], v[182:185]
	v_mfma_f32_16x16x32_bf16 v[120:123], v[94:97], v[120:123], v[90:93]
	v_mfma_f32_16x16x32_bf16 v[102:105], v[94:97], v[102:105], v[86:89]
	v_mfma_f32_16x16x32_bf16 v[98:101], v[94:97], v[98:101], v[82:85]
	ds_read_b64_tr_b16 v[212:213], v130 offset:8192
	ds_read_b64_tr_b16 v[194:195], v131 offset:8192
	ds_read_b64_tr_b16 v[90:91], v132 offset:8192
	ds_read_b64_tr_b16 v[82:83], v133 offset:8192
	ds_read_b64_tr_b16 v[86:87], v134 offset:8192
	ds_read_b64_tr_b16 v[94:95], v135 offset:8192
	ds_read_b64_tr_b16 v[190:191], v136 offset:8192
	ds_read_b64_tr_b16 v[186:187], v137 offset:8192
	s_waitcnt lgkmcnt(0)
	ds_read_b64_tr_b16 v[214:215], v138 offset:8192
	ds_read_b64_tr_b16 v[196:197], v139 offset:8192
	ds_read_b64_tr_b16 v[92:93], v140 offset:8192
	ds_read_b64_tr_b16 v[84:85], v141 offset:8192
	ds_read_b64_tr_b16 v[88:89], v142 offset:8192
	ds_read_b64_tr_b16 v[96:97], v143 offset:8192
	ds_read_b64_tr_b16 v[192:193], v144 offset:8192
	ds_read_b64_tr_b16 v[188:189], v145 offset:8192
	s_waitcnt lgkmcnt(0)
	s_waitcnt lgkmcnt(0)
	v_mfma_f32_16x16x32_bf16 v[106:109], v[220:223], v[212:215], v[106:109]
	v_mfma_f32_16x16x32_bf16 v[110:113], v[220:223], v[194:197], v[110:113]
	v_mfma_f32_16x16x32_bf16 v[90:93], v[220:223], v[90:93], v[172:175]
	v_mfma_f32_16x16x32_bf16 v[82:85], v[220:223], v[82:85], v[176:179]
	v_mfma_f32_16x16x32_bf16 v[86:89], v[220:223], v[86:89], v[182:185]
	v_mfma_f32_16x16x32_bf16 v[94:97], v[220:223], v[94:97], v[120:123]
	v_mfma_f32_16x16x32_bf16 v[102:105], v[220:223], v[190:193], v[102:105]
	v_mfma_f32_16x16x32_bf16 v[98:101], v[220:223], v[186:189], v[98:101]
	s_cbranch_scc1 .LBB0_952
	v_mov_b32_e32 v159, v118
	v_mov_b32_e32 v160, v117
	s_branch .LBB0_928
